# QKV and up-projection GEMM phases: workgroups that own one unit fewer (a whole round of slack) and have bit 3 of their id set start about half a unit late, so their epilogue stores overlap the other w
# speedup vs baseline: 1.0223x; 1.0058x over previous
; #define LAS __attribute__((address_space(3)))
; __device__ __forceinline__ unsigned xb_add(unsigned* p, unsigned v) { return __hip_atomic_fetch_add(p, v, __ATOMIC_RELAXED, __HIP_MEMORY_SCOPE_AGENT); }
; __device__ __forceinline__ unsigned xb_xcc_id() { return (unsigned)__builtin_amdgcn_s_getreg((3 << 11) | 20) & 0xFu; }
; __device__ __forceinline__ XcdBarrier xcd_barrier_post(unsigned* bar, volatile LAS unsigned* st) {
;     XcdBarrier b; b.bar = bar; b.x = xb_xcc_id(); b.st = st;
;     if (threadIdx.x == 0) (void)xb_add(&bar[XB_XCNT(b.x)], 1u);
;     return b;
; }
; __global__ void __launch_bounds__(NWAVES * 64, 2) hymba_fwd(Args A) {
;     ...
;     grid.sync();
;     XcdBarrier bar = xcd_barrier_post((unsigned*)ws, bst);
;     {
;         pg8::Gemm g{(const pg8::bf16_t*)(ws + WS_XA), (const pg8::bf16_t*)(ws + WS_W1), M1, DIN, DM, DM};
;         pg8::StaticOrder S; S.init(M1, DIN, G, bx);
;         pg8::Epi1 E{(const float*)(ws + WS_RS1), (const float*)(ws + WS_ROPE), A.out, (pg8::bf16_t*)(ws + WS_QD), (pg8::bf16_t*)(ws + WS_QS), (pg8::bf16_t*)(ws + WS_KD), (pg8::bf16_t*)(ws + WS_KS),
;                     (pg8::bf16_t*)(ws + WS_VDT), (pg8::bf16_t*)(ws + WS_VST)};
;         pg8::gemm_phase<pg8::Epi1, pg8::StaticOrder, true, true>(lds, g, S, E);
.LBB0_102:
	s_or_b64 exec, exec, s[0:1]
	s_barrier
	s_cmp_lt_u32 s22, 36
	s_cbranch_scc1 .Lstag_p1
	s_bitcmp1_b32 s22, 3
	s_cbranch_scc0 .Lstag_p1
	s_sleep 127
	s_sleep 127
	s_sleep 127
.Lstag_p1:
	s_getreg_b32 s0, hwreg(HW_REG_XCC_ID, 0, 4)
	s_and_b32 s33, s0, 15
	s_and_saveexec_b64 s[0:1], s[30:31]
	s_cbranch_execz .LBB0_105
	s_mov_b64 s[2:3], exec
	v_mbcnt_lo_u32_b32 v0, s2, 0
	v_mbcnt_hi_u32_b32 v0, s3, v0
	v_cmp_eq_u32_e32 vcc, 0, v0
	s_and_b64 s[4:5], exec, vcc
	s_mov_b64 exec, s[4:5]
	s_cbranch_execz .LBB0_105
	s_lshl_b32 s4, s33, 8
	s_bcnt1_i32_b64 s2, s[2:3]
	v_mov_b32_e32 v0, s4
	v_mov_b32_e32 v1, s2
	global_atomic_add v0, v1, s[80:81] offset:1024

; #define PG8_BAR __builtin_amdgcn_s_barrier()
; template <class Epi, class Sched, bool ALIGN_EPI = false, bool SP2 = false>
; __device__ __forceinline__ void gemm_phase(PG8_LAS unsigned char* lds, const Gemm g, const Sched& S, const Epi& E) {
;     int tid_ = threadIdx.x; asm volatile("" : "+v"(tid_));
;     const int tid = tid_, wid = __builtin_amdgcn_readfirstlane(tid >> 6), lane = tid & 63, wr = wid >> 2, wc = wid & 3, fr = lane & 15, fq = lane >> 4;
;     const int K = g.ld, nt = g.K / BK;
;     unsigned voffA[2], voffB[2];
; #pragma unroll
;     for (int i = 0; i < 2; ++i) { int R, C; stage_rc(tid * 16 + i * 8192, R, C); const int Rb = Epi::PERM ? ((R & ~31) + perm32(R & 31)) : R;
;         voffA[i] = (unsigned)(R * K + C) * 2u; voffB[i] = (unsigned)(Rb * K + C) * 2u; }
;     const size_t kstep = (size_t)(BK * 2);
;     const size_t hstep = (size_t)HALF * K * 2;
;     const size_t tstep = 2 * hstep;
;     const unsigned ldsw = (unsigned)wid * 1024u;
;     const int aoff = lds_byte(wr * 64 + fr, fq * 8), boff = lds_byte(wc * 32 + fr, fq * 8);
;     ...
;     Unit cur, nxt; int ui = 0;
;     if (!S.next(0, cur)) return;
;     f32x4 acc[2][2][4][2];
; #pragma unroll
;     for (int a = 0; a < 2; ++a)
; #pragma unroll
;         for (int b = 0; b < 2; ++b)
; #pragma unroll
;             for (int m = 0; m < 4; ++m)
; #pragma unroll
;                 for (int n = 0; n < 2; ++n) acc[a][b][m][n] = (f32x4){0.f, 0.f, 0.f, 0.f};
;     bf16x8 At[4][2], B0[2][2], B1[2][2];
;     const char* cA = (const char*)g.A + (size_t)cur.pm * tstep + (size_t)cur.kofs * 2; const char* cB = (const char*)g.Bt + (size_t)cur.pn * tstep + (size_t)cur.kofs * 2;
;     S.a_ready(cur);
;     if constexpr (SP2) {
;         PG8_STAGE(PG8_SB(0, 0), cB, voffB); PG8_STAGE(PG8_SB(0, 1), cB + hstep, voffB); PG8_STAGE(PG8_SA(0, 0), cA, voffA); PG8_STAGE(PG8_SA(0, 1), cA + hstep, voffA);
;         if (wr == 1) PG8_BAR;
;         PG8_WAIT_V(2); PG8_BAR;
;         PG8_STAGE(PG8_SB(1, 0), cB + kstep, voffB); PG8_STAGE(PG8_SA(1, 0), cA + kstep, voffA); PG8_STAGE(PG8_SB(1, 1), cB + hstep + kstep, voffB);
;         PG8_WAIT_V(6); PG8_BAR;
;     } else {
;         PG8_STAGE(PG8_SB(0, 0), cB, voffB); PG8_STAGE(PG8_SA(0, 0), cA, voffA); PG8_STAGE(PG8_SB(0, 1), cB + hstep, voffB); PG8_STAGE(PG8_SA(0, 1), cA + hstep, voffA);
;         if (wr == 1) PG8_BAR;
;         PG8_WAIT_V(4); PG8_BAR;
.LBB0_746:
	s_or_b64 exec, exec, s[0:1]
	v_mov_b32_e32 v9, v138
	s_waitcnt lgkmcnt(0)
	s_barrier
	s_cmp_lt_u32 s22, 32
	s_cbranch_scc1 .Lstag_p4
	s_bitcmp1_b32 s22, 3
	s_cbranch_scc0 .Lstag_p4
	s_sleep 127
	s_sleep 127
	s_sleep 127
.Lstag_p4:
	s_cmpk_gt_i32 s22, 0x41f
	v_readfirstlane_b32 s5, v9
	s_cbranch_scc1 .LBB0_762
	v_lshlrev_b32_e32 v0, 4, v9
	v_add_u32_e32 v1, 0x2000, v0
	v_ashrrev_i32_e32 v2, 31, v1
	v_lshrrev_b32_e32 v2, 22, v2
	v_add_u32_e32 v2, v1, v2
	v_ashrrev_i32_e32 v8, 10, v2
	v_mul_i32_i24_e32 v2, 0x400, v8
	v_sub_u32_e32 v1, v1, v2
	v_lshrrev_b32_e32 v2, 4, v1
	v_bitop3_b32 v1, v2, v1, 32 bitop3:0x6c
	v_ashrrev_i32_e32 v2, 31, v1
	v_lshrrev_b32_e32 v2, 26, v2
	v_add_u32_e32 v2, v1, v2
	v_lshlrev_b32_e32 v3, 3, v8
	v_ashrrev_i32_e32 v10, 6, v2
	v_and_b32_e32 v3, -16, v3
	v_add_u32_e32 v3, v10, v3
	v_and_b32_e32 v4, 3, v10
	s_mov_b32 s0, 0x1fffe0
	v_lshrrev_b32_e32 v5, 2, v3
	v_lshlrev_b32_e32 v6, 1, v3
	v_and_b32_e32 v2, 0xc0, v2
	v_and_or_b32 v4, v3, s0, v4
	v_and_b32_e32 v5, 4, v5
	v_and_b32_e32 v6, 24, v6
	v_sub_u32_e32 v1, v1, v2
	v_mov_b32_e32 v2, 1
	v_or3_b32 v4, v4, v5, v6
	v_lshlrev_b32_e32 v5, 5, v8
	v_ashrrev_i16_sdwa v1, v2, sext(v1) dst_sel:DWORD dst_unused:UNUSED_PAD src0_sel:DWORD src1_sel:BYTE_0
	v_and_b32_e32 v5, 32, v5
	v_bfe_i32 v11, v1, 0, 16
	v_add_lshl_u32 v1, v5, v11, 1
	v_lshl_add_u32 v128, v4, 11, v1
	v_lshl_add_u32 v130, v3, 11, v1
	v_bfe_i32 v1, v9, 27, 1
	v_lshrrev_b32_e32 v1, 22, v1
	v_add_u32_e32 v1, v0, v1
	v_and_b32_e32 v1, 0xfffffc00, v1
	v_sub_u32_e32 v0, v0, v1
	v_lshrrev_b32_e32 v1, 4, v0
	v_ashrrev_i32_e32 v3, 31, v9
	v_bitop3_b32 v0, v1, v0, 32 bitop3:0x6c
	v_lshrrev_b32_e32 v3, 26, v3
	v_ashrrev_i32_e32 v1, 31, v0
	v_add_u32_e32 v3, v9, v3
	v_lshrrev_b32_e32 v1, 26, v1
	v_ashrrev_i32_e32 v13, 6, v3
	v_add_u32_e32 v1, v0, v1
	v_lshlrev_b32_e32 v3, 3, v13
	v_ashrrev_i32_e32 v12, 6, v1
	v_and_b32_e32 v3, -16, v3
	s_add_u32 s23, s80, 0x900000
	v_add_u32_e32 v3, v12, v3
	v_and_b32_e32 v4, 3, v12
	s_addc_u32 s33, s81, 0
	v_and_or_b32 v4, v3, s0, v4
	s_ashr_i32 s0, s22, 31
	s_lshr_b32 s0, s0, 29
	s_add_i32 s0, s22, s0
	s_ashr_i32 s14, s5, 6
	s_ashr_i32 s1, s0, 3
	s_and_b32 s0, s0, -8
	s_ashr_i32 s6, s5, 8
	s_lshl_b32 s38, s14, 10
	s_sub_i32 s0, s22, s0
	s_cmp_lt_i32 s0, 0
	s_movk_i32 s39, 0x85
	s_cselect_b32 s4, s39, 0x84
	s_mul_i32 s0, s0, s4
	s_add_i32 s0, s0, s1
	s_ashr_i32 s1, s0, 31
	s_lshr_b32 s1, s1, 25
	s_add_i32 s1, s0, s1
	v_lshrrev_b32_e32 v5, 2, v3
	v_lshlrev_b32_e32 v6, 1, v3
	v_and_b32_e32 v1, 0xc0, v1
	s_ashr_i32 s1, s1, 7
	v_and_b32_e32 v5, 4, v5
	v_and_b32_e32 v6, 24, v6
	v_sub_u32_e32 v0, v0, v1
	s_lshl_b32 s7, s1, 3
	v_or3_b32 v4, v4, v5, v6
	v_lshlrev_b32_e32 v5, 5, v13
	v_ashrrev_i16_sdwa v0, v2, sext(v0) dst_sel:DWORD dst_unused:UNUSED_PAD src0_sel:DWORD src1_sel:BYTE_0
	s_sub_i32 s4, 0x42, s7
	s_lshl_b32 s1, s1, 7
	v_and_b32_e32 v5, 32, v5
	v_bfe_i32 v14, v0, 0, 16
	s_min_u32 s12, s4, 8
	s_sub_i32 s13, s0, s1
	v_add_lshl_u32 v0, v5, v14, 1
	s_sext_i32_i8 s0, s13
	v_cvt_f32_ubyte0_e32 v2, s12
	v_lshl_add_u32 v132, v4, 11, v0
	v_cvt_f32_i32_e32 v1, s0
	v_rcp_iflag_f32_e32 v4, v2
	v_lshl_add_u32 v134, v3, 11, v0
	s_ashr_i32 s0, s0, 30
	s_or_b32 s4, s0, 1
	v_mul_f32_e32 v0, v1, v4
	v_trunc_f32_e32 v0, v0
	v_fma_f32 v1, -v0, v2, v1
	v_cvt_i32_f32_e32 v0, v0
	v_cmp_ge_f32_e64 s[0:1], |v1|, v2
	s_and_b64 s[0:1], s[0:1], exec
	s_cselect_b32 s0, s4, 0
	v_readfirstlane_b32 s1, v0
	s_add_i32 s4, s1, s0
	s_mul_i32 s0, s4, s12
	s_sub_i32 s0, s13, s0
	s_sext_i32_i8 s0, s0
	s_add_i32 s0, s7, s0
	s_ashr_i32 s1, s0, 31
	s_bfe_i64 s[16:17], s[4:5], 0x80000
	s_lshl_b64 s[12:13], s[0:1], 19
	s_lshl_b64 s[16:17], s[16:17], 19
	s_add_u32 s34, s23, s16
	s_addc_u32 s35, s33, s17
	s_add_i32 s40, s38, 0
	s_add_i32 m0, s40, 0x10000
	v_mov_b32_e32 v141, 0
	global_load_lds_dwordx4 v132, s[34:35]
	s_add_i32 m0, s40, 0x12000
	s_add_u32 s16, s34, 0x40000
	global_load_lds_dwordx4 v128, s[34:35]
	s_addc_u32 s17, s35, 0
	s_add_i32 m0, s40, 0x14000
	v_mov_b32_e32 v133, v141
	global_load_lds_dwordx4 v132, s[16:17]
	s_add_i32 m0, s40, 0x16000
	s_add_u32 s30, s8, s12
	s_addc_u32 s31, s9, s13
	s_add_i32 s41, s40, 0x2000
	global_load_lds_dwordx4 v128, s[16:17]
	s_mov_b32 m0, s40
	s_add_u32 s12, s30, 0x40000
	global_load_lds_dwordx4 v134, s[30:31]
	s_mov_b32 m0, s41
	s_addc_u32 s13, s31, 0
	s_add_i32 s42, s40, 0x4000
	global_load_lds_dwordx4 v130, s[30:31]
	s_mov_b32 m0, s42
	s_add_i32 s43, s40, 0x6000
	global_load_lds_dwordx4 v134, s[12:13]
	s_mov_b32 m0, s43
	v_mov_b32_e32 v129, v141
	global_load_lds_dwordx4 v130, s[12:13]
	v_mov_b32_e32 v135, v141
	v_mov_b32_e32 v131, v141
	s_cmp_eq_u32 s6, 1
	s_mov_b32 s7, 0
	v_lshl_add_u64 v[6:7], s[34:35], 0, v[132:133]
	v_lshl_add_u64 v[4:5], s[34:35], 0, v[128:129]
	v_lshl_add_u64 v[0:1], s[30:31], 0, v[134:135]
	s_cselect_b64 s[12:13], -1, 0
	s_cmp_lg_u32 s6, 1
	v_lshl_add_u64 v[2:3], s[30:31], 0, v[130:131]
	s_cbranch_scc1 .LBB0_749
	s_barrier
